# phase C stage 1: wave-uniform match test moved above the per-i setup so non-matching i skip it
# speedup vs baseline: 1.0138x; 1.0043x over previous
; #define LAS __attribute__((address_space(3)))
; DI void hgrn_phase_c(const Params& p, LAS unsigned char* lds) {
;     ...
;         {
;             int cnt = 0;
;             for (int i = 0; i < 8; ++i)
;                 for (int j = 0; j <= i; ++j, ++cnt) {
;                     if ((cnt & 7) != wsc) continue;
;                     f32x4 acc = (f32x4){0.f, 0.f, 0.f, 0.f};
; #pragma unroll
;                     for (int ks = 0; ks < 4; ++ks) {
;                         const bf16x8 kf = *(LAS const bf16x8*)(lds + R2 + (16 * j + l15) * RS + (32 * ks + 8 * g4) * 2);
;                         bf16x8 qf = *(LAS const bf16x8*)(lds + R1 + (16 * i + l15) * RS + (32 * ks + 8 * g4) * 2);
;                         if (i != j) {
;                             LAS const float* ep = (LAS const float*)(lds + OFF_ET) + (i * (i - 1) / 2 + j) * 128 + 32 * ks + 8 * g4;
.LBB0_435:
	s_add_i32 s58, s3, 1
	s_sub_i32 s59, s35, s97
	s_and_b32 s59, s59, 7
	s_cmp_gt_u32 s59, s3
	s_cbranch_scc1 .LBB0_434
	s_add_i32 s0, s3, -1
	s_mul_i32 s0, s0, s3
	s_lshr_b32 s1, s0, 31
	s_add_i32 s0, s0, s1
	v_lshl_or_b32 v48, s3, 4, v137
	s_lshl_b32 s0, s0, 8
	v_mul_lo_u32 v48, v48, s70
	s_and_b32 s0, s0, 0xfffffe00
	v_or_b32_e32 v170, s0, v153
	s_add_i32 s58, s3, 1
	v_add_u32_e32 v171, v148, v48
	v_mov_b32_e32 v172, v154
	v_mov_b32_e32 v173, v169
	s_lshl_b32 s0, s59, 5
	v_add_u32_e32 v173, s0, v173
	s_lshl_b32 s0, s59, 9
	v_add_u32_e32 v170, s0, v170
	s_mul_i32 s0, s59, 0x1100
	v_add_u32_e32 v172, s0, v172
	s_branch .Lc_s1_body
